# v001 plus non-temporal policy on the MLP-up epilogue stores (u is written once, read once by the next phase)
# speedup vs baseline: 1.0024x; 1.0024x over previous
.LBB0_564:
	v_lshl_add_u32 v150, s21, 8, v141
	v_ashrrev_i32_e32 v151, 31, v150
	s_and_b64 s[12:13], s[40:41], exec
	s_cselect_b32 s12, s48, s21
	v_lshl_add_u32 v238, s12, 8, v141
	v_mov_b32_e32 v239, 0
	v_lshl_add_u64 v[238:239], v[238:239], 2, s[4:5]
	s_mov_b64 s[12:13], 0x100000
	s_waitcnt vmcnt(8)
	v_fmamk_f32 v140, v240, 0x3a800000, v225
	v_rsq_f32_e32 v160, v140
	v_fmamk_f32 v144, v241, 0x3a800000, v225
	v_rsq_f32_e32 v158, v144
	v_fmamk_f32 v153, v244, 0x3a800000, v225
	v_pk_mul_f32 v[122:123], v[122:123], v[160:161] op_sel_hi:[1,0]
	v_pk_mul_f32 v[126:127], v[126:127], v[160:161] op_sel_hi:[1,0]
	v_pk_mul_f32 v[124:125], v[124:125], v[160:161] op_sel_hi:[1,0]
	v_max_f32_e32 v122, 0, v122
	v_pk_mul_f32 v[128:129], v[128:129], v[160:161] op_sel_hi:[1,0]
	v_max_f32_e32 v123, 0, v123
	v_max_f32_e32 v124, 0, v124
	v_max_f32_e32 v126, 0, v126
	v_max_f32_e32 v125, 0, v125
	v_pk_mul_f32 v[114:115], v[114:115], v[160:161] op_sel_hi:[1,0]
	v_mul_f32_e32 v126, v126, v126
	v_mul_f32_e32 v125, v125, v125
	v_pk_mul_f32 v[118:119], v[118:119], v[160:161] op_sel_hi:[1,0]
	v_pk_mul_f32 v[116:117], v[116:117], v[160:161] op_sel_hi:[1,0]
	v_max_f32_e32 v114, 0, v114
	v_pk_mul_f32 v[120:121], v[120:121], v[160:161] op_sel_hi:[1,0]
	v_max_f32_e32 v115, 0, v115
	v_max_f32_e32 v116, 0, v116
	v_max_f32_e32 v118, 0, v118
	v_max_f32_e32 v117, 0, v117
	v_mul_f32_e32 v118, v118, v118
	v_mul_f32_e32 v117, v117, v117
	v_pk_mul_f32 v[106:107], v[106:107], v[158:159] op_sel_hi:[1,0]
	v_pk_mul_f32 v[110:111], v[110:111], v[158:159] op_sel_hi:[1,0]
	v_pk_mul_f32 v[108:109], v[108:109], v[158:159] op_sel_hi:[1,0]
	v_max_f32_e32 v106, 0, v106
	v_pk_mul_f32 v[112:113], v[112:113], v[158:159] op_sel_hi:[1,0]
	v_max_f32_e32 v107, 0, v107
	v_max_f32_e32 v108, 0, v108
	v_fmamk_f32 v146, v242, 0x3a800000, v225
	v_max_f32_e32 v110, 0, v110
	v_max_f32_e32 v109, 0, v109
	v_pk_mul_f32 v[98:99], v[98:99], v[158:159] op_sel_hi:[1,0]
	v_rsq_f32_e32 v154, v146
	v_mul_f32_e32 v110, v110, v110
	v_mul_f32_e32 v109, v109, v109
	v_pk_mul_f32 v[102:103], v[102:103], v[158:159] op_sel_hi:[1,0]
	v_pk_mul_f32 v[100:101], v[100:101], v[158:159] op_sel_hi:[1,0]
	v_max_f32_e32 v98, 0, v98
	v_pk_mul_f32 v[104:105], v[104:105], v[158:159] op_sel_hi:[1,0]
	v_max_f32_e32 v99, 0, v99
	v_max_f32_e32 v100, 0, v100
	v_max_f32_e32 v102, 0, v102
	v_max_f32_e32 v101, 0, v101
	v_mul_f32_e32 v102, v102, v102
	v_mul_f32_e32 v101, v101, v101
	v_fmamk_f32 v148, v243, 0x3a800000, v225
	v_fmamk_f32 v155, v245, 0x3a800000, v225
	v_pk_mul_f32 v[90:91], v[90:91], v[154:155] op_sel_hi:[1,0]
	v_pk_mul_f32 v[94:95], v[94:95], v[154:155] op_sel_hi:[1,0]
	v_pk_mul_f32 v[92:93], v[92:93], v[154:155] op_sel_hi:[1,0]
	v_max_f32_e32 v90, 0, v90
	v_pk_mul_f32 v[96:97], v[96:97], v[154:155] op_sel_hi:[1,0]
	v_max_f32_e32 v91, 0, v91
	v_max_f32_e32 v92, 0, v92
	v_max_f32_e32 v94, 0, v94
	v_max_f32_e32 v93, 0, v93
	v_pk_mul_f32 v[82:83], v[82:83], v[154:155] op_sel_hi:[1,0]
	v_mul_f32_e32 v94, v94, v94
	v_mul_f32_e32 v93, v93, v93
	v_pk_mul_f32 v[86:87], v[86:87], v[154:155] op_sel_hi:[1,0]
	v_pk_mul_f32 v[84:85], v[84:85], v[154:155] op_sel_hi:[1,0]
	v_max_f32_e32 v82, 0, v82
	v_pk_mul_f32 v[88:89], v[88:89], v[154:155] op_sel_hi:[1,0]
	v_max_f32_e32 v83, 0, v83
	v_max_f32_e32 v84, 0, v84
	v_max_f32_e32 v86, 0, v86
	v_max_f32_e32 v85, 0, v85
	v_mul_f32_e32 v86, v86, v86
	v_mul_f32_e32 v85, v85, v85
	v_rsq_f32_e32 v146, v155
	v_fmamk_f32 v156, v246, 0x3a800000, v225
	v_rsq_f32_e32 v144, v156
	v_fmamk_f32 v142, v247, 0x3a800000, v225
	v_rsq_f32_e32 v140, v142
	global_load_dword v240, v[238:239], off
	global_load_dword v241, v[238:239], off offset:64
	global_load_dword v242, v[238:239], off offset:128
	global_load_dword v243, v[238:239], off offset:192
	global_load_dword v244, v[238:239], off offset:512
	global_load_dword v245, v[238:239], off offset:576
	global_load_dword v246, v[238:239], off offset:640
	global_load_dword v247, v[238:239], off offset:704
	v_lshl_or_b32 v142, s20, 8, v147
	v_ashrrev_i32_e32 v143, 31, v142
	v_lshlrev_b64 v[156:157], 13, v[150:151]
	v_mul_f32_e32 v151, v122, v122
	v_max_f32_e32 v122, 0, v127
	v_lshl_add_u64 v[162:163], s[42:43], 0, v[156:157]
	v_lshlrev_b64 v[156:157], 1, v[142:143]
	v_mul_f32_e32 v122, v122, v122
	v_mul_f32_e32 v127, v123, v123
	v_max_f32_e32 v123, 0, v128
	v_mul_f32_e32 v128, v124, v124
	v_max_f32_e32 v124, 0, v129
	v_lshl_add_u64 v[142:143], v[162:163], 0, v[156:157]
	v_mul_f32_e32 v123, v123, v123
	v_mul_f32_e32 v124, v124, v124
	v_cvt_pk_bf16_f32 v122, v126, v122
	v_cvt_pk_bf16_f32 v123, v123, v124
	v_cvt_pk_bf16_f32 v124, v151, v127
	v_cvt_pk_bf16_f32 v125, v128, v125
	flat_store_dwordx4 v[142:143], v[122:125] nt
	v_rsq_f32_e32 v152, v148
	v_rsq_f32_e32 v148, v153
	v_mul_f32_e32 v122, v114, v114
	v_max_f32_e32 v114, 0, v119
	v_mul_f32_e32 v114, v114, v114
	v_mul_f32_e32 v119, v115, v115
	v_max_f32_e32 v115, 0, v120
	v_mul_f32_e32 v120, v116, v116
	v_max_f32_e32 v116, 0, v121
	v_mul_f32_e32 v115, v115, v115
	v_mul_f32_e32 v116, v116, v116
	v_cvt_pk_bf16_f32 v114, v118, v114
	v_cvt_pk_bf16_f32 v115, v115, v116
	v_cvt_pk_bf16_f32 v116, v122, v119
	v_cvt_pk_bf16_f32 v117, v120, v117
	flat_store_dwordx4 v[142:143], v[114:117] offset:256 nt
	v_pk_mul_f32 v[74:75], v[74:75], v[152:153] op_sel_hi:[1,0]
	v_pk_mul_f32 v[78:79], v[78:79], v[152:153] op_sel_hi:[1,0]
	v_or_b32_e32 v114, 16, v150
	v_ashrrev_i32_e32 v115, 31, v114
	v_lshlrev_b64 v[114:115], 13, v[114:115]
	v_mul_f32_e32 v116, v106, v106
	v_max_f32_e32 v106, 0, v111
	v_lshl_add_u64 v[114:115], s[42:43], 0, v[114:115]
	v_mul_f32_e32 v106, v106, v106
	v_mul_f32_e32 v111, v107, v107
	v_max_f32_e32 v107, 0, v112
	v_mul_f32_e32 v112, v108, v108
	v_max_f32_e32 v108, 0, v113
	v_lshl_add_u64 v[114:115], v[114:115], 0, v[156:157]
	v_mul_f32_e32 v107, v107, v107
	v_mul_f32_e32 v108, v108, v108
	v_cvt_pk_bf16_f32 v106, v110, v106
	v_cvt_pk_bf16_f32 v107, v107, v108
	v_cvt_pk_bf16_f32 v108, v116, v111
	v_cvt_pk_bf16_f32 v109, v112, v109
	flat_store_dwordx4 v[114:115], v[106:109] nt
	v_pk_mul_f32 v[76:77], v[76:77], v[152:153] op_sel_hi:[1,0]
	v_max_f32_e32 v74, 0, v74
	v_mul_f32_e32 v106, v98, v98
	v_max_f32_e32 v98, 0, v103
	v_mul_f32_e32 v98, v98, v98
	v_mul_f32_e32 v103, v99, v99
	v_max_f32_e32 v99, 0, v104
	v_mul_f32_e32 v104, v100, v100
	v_max_f32_e32 v100, 0, v105
	v_mul_f32_e32 v99, v99, v99
	v_mul_f32_e32 v100, v100, v100
	v_cvt_pk_bf16_f32 v98, v102, v98
	v_cvt_pk_bf16_f32 v99, v99, v100
	v_cvt_pk_bf16_f32 v100, v106, v103
	v_cvt_pk_bf16_f32 v101, v104, v101
	flat_store_dwordx4 v[114:115], v[98:101] offset:256 nt
	v_pk_mul_f32 v[80:81], v[80:81], v[152:153] op_sel_hi:[1,0]
	v_max_f32_e32 v75, 0, v75
	v_or_b32_e32 v98, 32, v150
	v_ashrrev_i32_e32 v99, 31, v98
	v_lshlrev_b64 v[98:99], 13, v[98:99]
	v_mul_f32_e32 v100, v90, v90
	v_max_f32_e32 v90, 0, v95
	v_lshl_add_u64 v[98:99], s[42:43], 0, v[98:99]
	v_mul_f32_e32 v90, v90, v90
	v_mul_f32_e32 v95, v91, v91
	v_max_f32_e32 v91, 0, v96
	v_mul_f32_e32 v96, v92, v92
	v_max_f32_e32 v92, 0, v97
	v_lshl_add_u64 v[98:99], v[98:99], 0, v[156:157]
	v_mul_f32_e32 v91, v91, v91
	v_mul_f32_e32 v92, v92, v92
	v_cvt_pk_bf16_f32 v90, v94, v90
	v_cvt_pk_bf16_f32 v91, v91, v92
	v_cvt_pk_bf16_f32 v92, v100, v95
	v_cvt_pk_bf16_f32 v93, v96, v93
	flat_store_dwordx4 v[98:99], v[90:93] nt
	v_max_f32_e32 v76, 0, v76
	v_max_f32_e32 v78, 0, v78
	v_mul_f32_e32 v90, v82, v82
	v_max_f32_e32 v82, 0, v87
	v_mul_f32_e32 v82, v82, v82
	v_mul_f32_e32 v87, v83, v83
	v_max_f32_e32 v83, 0, v88
	v_mul_f32_e32 v88, v84, v84
	v_max_f32_e32 v84, 0, v89
	v_mul_f32_e32 v83, v83, v83
	v_mul_f32_e32 v84, v84, v84
	v_cvt_pk_bf16_f32 v82, v86, v82
	v_cvt_pk_bf16_f32 v83, v83, v84
	v_cvt_pk_bf16_f32 v84, v90, v87
	v_cvt_pk_bf16_f32 v85, v88, v85
	flat_store_dwordx4 v[98:99], v[82:85] offset:256 nt
	v_max_f32_e32 v77, 0, v77
	v_pk_mul_f32 v[68:69], v[68:69], v[152:153] op_sel_hi:[1,0]
	v_or_b32_e32 v82, 48, v150
	v_ashrrev_i32_e32 v83, 31, v82
	v_lshlrev_b64 v[82:83], 13, v[82:83]
	v_mul_f32_e32 v84, v74, v74
	v_max_f32_e32 v74, 0, v79
	v_lshl_add_u64 v[82:83], s[42:43], 0, v[82:83]
	v_mul_f32_e32 v74, v74, v74
	v_mul_f32_e32 v79, v75, v75
	v_max_f32_e32 v75, 0, v80
	v_mul_f32_e32 v80, v76, v76
	v_max_f32_e32 v76, 0, v81
	v_pk_mul_f32 v[66:67], v[66:67], v[152:153] op_sel_hi:[1,0]
	v_lshl_add_u64 v[82:83], v[82:83], 0, v[156:157]
	v_mul_f32_e32 v78, v78, v78
	v_mul_f32_e32 v75, v75, v75
	v_mul_f32_e32 v76, v76, v76
	v_mul_f32_e32 v77, v77, v77
	v_cvt_pk_bf16_f32 v74, v78, v74
	v_pk_mul_f32 v[72:73], v[72:73], v[152:153] op_sel_hi:[1,0]
	v_pk_mul_f32 v[70:71], v[70:71], v[152:153] op_sel_hi:[1,0]
	v_max_f32_e32 v66, 0, v66
	v_max_f32_e32 v67, 0, v67
	v_max_f32_e32 v68, 0, v68
	v_cvt_pk_bf16_f32 v75, v75, v76
	v_cvt_pk_bf16_f32 v76, v84, v79
	v_cvt_pk_bf16_f32 v77, v80, v77
	flat_store_dwordx4 v[82:83], v[74:77] nt
	v_max_f32_e32 v70, 0, v70
	v_max_f32_e32 v69, 0, v69
	v_mul_f32_e32 v74, v66, v66
	v_max_f32_e32 v66, 0, v71
	v_mul_f32_e32 v71, v67, v67
	v_max_f32_e32 v67, 0, v72
	v_mul_f32_e32 v72, v68, v68
	v_max_f32_e32 v68, 0, v73
	v_mul_f32_e32 v66, v66, v66
	v_mul_f32_e32 v67, v67, v67
	v_mul_f32_e32 v68, v68, v68
	v_pk_mul_f32 v[58:59], v[58:59], v[148:149] op_sel_hi:[1,0]
	v_mul_f32_e32 v70, v70, v70
	v_mul_f32_e32 v69, v69, v69
	v_cvt_pk_bf16_f32 v66, v70, v66
	v_cvt_pk_bf16_f32 v67, v67, v68
	v_cvt_pk_bf16_f32 v68, v74, v71
	v_pk_mul_f32 v[62:63], v[62:63], v[148:149] op_sel_hi:[1,0]
	v_pk_mul_f32 v[60:61], v[60:61], v[148:149] op_sel_hi:[1,0]
	v_max_f32_e32 v58, 0, v58
	v_cvt_pk_bf16_f32 v69, v72, v69
	flat_store_dwordx4 v[82:83], v[66:69] offset:256 nt
	v_pk_mul_f32 v[64:65], v[64:65], v[148:149] op_sel_hi:[1,0]
	v_max_f32_e32 v62, 0, v62
	v_mul_f32_e32 v68, v58, v58
	v_max_f32_e32 v58, 0, v63
	v_max_f32_e32 v59, 0, v59
	v_max_f32_e32 v60, 0, v60
	v_lshl_add_u64 v[66:67], v[142:143], 0, s[12:13]
	v_mul_f32_e32 v62, v62, v62
	v_mul_f32_e32 v58, v58, v58
	v_mul_f32_e32 v63, v59, v59
	v_max_f32_e32 v59, 0, v64
	v_mul_f32_e32 v64, v60, v60
	v_max_f32_e32 v60, 0, v65
	s_mov_b32 s12, 0x100000
	v_mul_f32_e32 v59, v59, v59
	v_max_f32_e32 v61, 0, v61
	v_mul_f32_e32 v60, v60, v60
	v_cvt_pk_bf16_f32 v58, v62, v58
	v_add_co_u32_e32 v62, vcc, s12, v142
	v_pk_mul_f32 v[52:53], v[52:53], v[148:149] op_sel_hi:[1,0]
	v_pk_mul_f32 v[50:51], v[50:51], v[148:149] op_sel_hi:[1,0]
	v_mul_f32_e32 v61, v61, v61
	v_cvt_pk_bf16_f32 v59, v59, v60
	v_cvt_pk_bf16_f32 v60, v68, v63
	v_addc_co_u32_e32 v63, vcc, 0, v143, vcc
	v_pk_mul_f32 v[56:57], v[56:57], v[148:149] op_sel_hi:[1,0]
	v_pk_mul_f32 v[54:55], v[54:55], v[148:149] op_sel_hi:[1,0]
	v_max_f32_e32 v50, 0, v50
	v_max_f32_e32 v51, 0, v51
	v_max_f32_e32 v52, 0, v52
	v_cvt_pk_bf16_f32 v61, v64, v61
	flat_store_dwordx4 v[62:63], v[58:61] nt
	v_max_f32_e32 v54, 0, v54
	v_max_f32_e32 v53, 0, v53
	v_mul_f32_e32 v58, v50, v50
	v_max_f32_e32 v50, 0, v55
	v_mul_f32_e32 v55, v51, v51
	v_max_f32_e32 v51, 0, v56
	v_mul_f32_e32 v56, v52, v52
	v_max_f32_e32 v52, 0, v57
	v_mul_f32_e32 v50, v50, v50
	v_mul_f32_e32 v51, v51, v51
	v_mul_f32_e32 v52, v52, v52
	v_pk_mul_f32 v[42:43], v[42:43], v[146:147] op_sel_hi:[1,0]
	v_mul_f32_e32 v54, v54, v54
	v_mul_f32_e32 v53, v53, v53
	v_cvt_pk_bf16_f32 v50, v54, v50
	v_cvt_pk_bf16_f32 v51, v51, v52
	v_cvt_pk_bf16_f32 v52, v58, v55
	v_pk_mul_f32 v[46:47], v[46:47], v[146:147] op_sel_hi:[1,0]
	v_pk_mul_f32 v[44:45], v[44:45], v[146:147] op_sel_hi:[1,0]
	v_max_f32_e32 v42, 0, v42
	v_cvt_pk_bf16_f32 v53, v56, v53
	flat_store_dwordx4 v[66:67], v[50:53] offset:256 nt
	s_mov_b64 s[12:13], 0x120000
	v_pk_mul_f32 v[48:49], v[48:49], v[146:147] op_sel_hi:[1,0]
	v_max_f32_e32 v46, 0, v46
	v_mul_f32_e32 v52, v42, v42
	v_max_f32_e32 v42, 0, v47
	v_max_f32_e32 v43, 0, v43
	v_max_f32_e32 v44, 0, v44
	v_lshl_add_u64 v[50:51], v[142:143], 0, s[12:13]
	v_mul_f32_e32 v46, v46, v46
	v_mul_f32_e32 v42, v42, v42
	v_mul_f32_e32 v47, v43, v43
	v_max_f32_e32 v43, 0, v48
	v_mul_f32_e32 v48, v44, v44
	v_max_f32_e32 v44, 0, v49
	s_mov_b32 s12, 0x120000
	v_mul_f32_e32 v43, v43, v43
	v_max_f32_e32 v45, 0, v45
	v_mul_f32_e32 v44, v44, v44
	v_cvt_pk_bf16_f32 v42, v46, v42
	v_add_co_u32_e32 v46, vcc, s12, v142
	v_pk_mul_f32 v[36:37], v[36:37], v[146:147] op_sel_hi:[1,0]
	v_pk_mul_f32 v[34:35], v[34:35], v[146:147] op_sel_hi:[1,0]
	v_mul_f32_e32 v45, v45, v45
	v_cvt_pk_bf16_f32 v43, v43, v44
	v_cvt_pk_bf16_f32 v44, v52, v47
	v_addc_co_u32_e32 v47, vcc, 0, v143, vcc
	v_pk_mul_f32 v[40:41], v[40:41], v[146:147] op_sel_hi:[1,0]
	v_pk_mul_f32 v[38:39], v[38:39], v[146:147] op_sel_hi:[1,0]
	v_max_f32_e32 v34, 0, v34
	v_max_f32_e32 v35, 0, v35
	v_max_f32_e32 v36, 0, v36
	v_cvt_pk_bf16_f32 v45, v48, v45
	flat_store_dwordx4 v[46:47], v[42:45] nt
	v_max_f32_e32 v38, 0, v38
	v_max_f32_e32 v37, 0, v37
	v_mul_f32_e32 v42, v34, v34
	v_max_f32_e32 v34, 0, v39
	v_mul_f32_e32 v39, v35, v35
	v_max_f32_e32 v35, 0, v40
	v_mul_f32_e32 v40, v36, v36
	v_max_f32_e32 v36, 0, v41
	v_mul_f32_e32 v34, v34, v34
	v_mul_f32_e32 v35, v35, v35
	v_mul_f32_e32 v36, v36, v36
	v_pk_mul_f32 v[26:27], v[26:27], v[144:145] op_sel_hi:[1,0]
	v_mul_f32_e32 v38, v38, v38
	v_mul_f32_e32 v37, v37, v37
	v_cvt_pk_bf16_f32 v34, v38, v34
	v_cvt_pk_bf16_f32 v35, v35, v36
	v_cvt_pk_bf16_f32 v36, v42, v39
	v_pk_mul_f32 v[30:31], v[30:31], v[144:145] op_sel_hi:[1,0]
	v_pk_mul_f32 v[28:29], v[28:29], v[144:145] op_sel_hi:[1,0]
	v_max_f32_e32 v26, 0, v26
	v_cvt_pk_bf16_f32 v37, v40, v37
	flat_store_dwordx4 v[50:51], v[34:37] offset:256 nt
	s_mov_b64 s[12:13], 0x140000
	v_pk_mul_f32 v[32:33], v[32:33], v[144:145] op_sel_hi:[1,0]
	v_max_f32_e32 v30, 0, v30
	v_mul_f32_e32 v36, v26, v26
	v_max_f32_e32 v26, 0, v31
	v_max_f32_e32 v27, 0, v27
	v_max_f32_e32 v28, 0, v28
	v_lshl_add_u64 v[34:35], v[142:143], 0, s[12:13]
	v_mul_f32_e32 v30, v30, v30
	v_mul_f32_e32 v26, v26, v26
	v_mul_f32_e32 v31, v27, v27
	v_max_f32_e32 v27, 0, v32
	v_mul_f32_e32 v32, v28, v28
	v_max_f32_e32 v28, 0, v33
	s_mov_b32 s12, 0x140000
	v_mul_f32_e32 v27, v27, v27
	v_max_f32_e32 v29, 0, v29
	v_mul_f32_e32 v28, v28, v28
	v_cvt_pk_bf16_f32 v26, v30, v26
	v_add_co_u32_e32 v30, vcc, s12, v142
	v_pk_mul_f32 v[20:21], v[20:21], v[144:145] op_sel_hi:[1,0]
	v_pk_mul_f32 v[18:19], v[18:19], v[144:145] op_sel_hi:[1,0]
	v_mul_f32_e32 v29, v29, v29
	v_cvt_pk_bf16_f32 v27, v27, v28
	v_cvt_pk_bf16_f32 v28, v36, v31
	v_addc_co_u32_e32 v31, vcc, 0, v143, vcc
	v_pk_mul_f32 v[24:25], v[24:25], v[144:145] op_sel_hi:[1,0]
	v_pk_mul_f32 v[22:23], v[22:23], v[144:145] op_sel_hi:[1,0]
	v_max_f32_e32 v18, 0, v18
	v_max_f32_e32 v19, 0, v19
	v_max_f32_e32 v20, 0, v20
	v_cvt_pk_bf16_f32 v29, v32, v29
	flat_store_dwordx4 v[30:31], v[26:29] nt
	v_max_f32_e32 v22, 0, v22
	v_max_f32_e32 v21, 0, v21
	v_mul_f32_e32 v26, v18, v18
	v_max_f32_e32 v18, 0, v23
	v_mul_f32_e32 v23, v19, v19
	v_max_f32_e32 v19, 0, v24
	v_mul_f32_e32 v24, v20, v20
	v_max_f32_e32 v20, 0, v25
	v_mul_f32_e32 v18, v18, v18
	v_mul_f32_e32 v19, v19, v19
	v_mul_f32_e32 v20, v20, v20
	v_pk_mul_f32 v[10:11], v[10:11], v[140:141] op_sel_hi:[1,0]
	v_mul_f32_e32 v22, v22, v22
	v_mul_f32_e32 v21, v21, v21
	v_cvt_pk_bf16_f32 v18, v22, v18
	v_cvt_pk_bf16_f32 v19, v19, v20
	v_cvt_pk_bf16_f32 v20, v26, v23
	v_pk_mul_f32 v[14:15], v[14:15], v[140:141] op_sel_hi:[1,0]
	v_pk_mul_f32 v[12:13], v[12:13], v[140:141] op_sel_hi:[1,0]
	v_max_f32_e32 v10, 0, v10
	v_cvt_pk_bf16_f32 v21, v24, v21
	flat_store_dwordx4 v[34:35], v[18:21] offset:256 nt
	s_mov_b64 s[12:13], 0x160000
	v_pk_mul_f32 v[16:17], v[16:17], v[140:141] op_sel_hi:[1,0]
	v_max_f32_e32 v14, 0, v14
	v_mul_f32_e32 v20, v10, v10
	v_max_f32_e32 v10, 0, v15
	v_max_f32_e32 v11, 0, v11
	v_max_f32_e32 v12, 0, v12
	v_lshl_add_u64 v[18:19], v[142:143], 0, s[12:13]
	v_mul_f32_e32 v14, v14, v14
	v_mul_f32_e32 v10, v10, v10
	v_mul_f32_e32 v15, v11, v11
	v_max_f32_e32 v11, 0, v16
	v_mul_f32_e32 v16, v12, v12
	v_max_f32_e32 v12, 0, v17
	s_mov_b32 s12, 0x160000
	v_mul_f32_e32 v11, v11, v11
	v_max_f32_e32 v13, 0, v13
	v_mul_f32_e32 v12, v12, v12
	v_cvt_pk_bf16_f32 v10, v14, v10
	v_add_co_u32_e32 v14, vcc, s12, v142
	v_pk_mul_f32 v[4:5], v[4:5], v[140:141] op_sel_hi:[1,0]
	v_pk_mul_f32 v[2:3], v[2:3], v[140:141] op_sel_hi:[1,0]
	v_mul_f32_e32 v13, v13, v13
	v_cvt_pk_bf16_f32 v11, v11, v12
	v_cvt_pk_bf16_f32 v12, v20, v15
	v_addc_co_u32_e32 v15, vcc, 0, v143, vcc
	v_pk_mul_f32 v[8:9], v[8:9], v[140:141] op_sel_hi:[1,0]
	v_pk_mul_f32 v[6:7], v[6:7], v[140:141] op_sel_hi:[1,0]
	v_max_f32_e32 v2, 0, v2
	v_max_f32_e32 v3, 0, v3
	v_max_f32_e32 v4, 0, v4
	v_cvt_pk_bf16_f32 v13, v16, v13
	flat_store_dwordx4 v[14:15], v[10:13] nt
	v_max_f32_e32 v5, 0, v5
	v_max_f32_e32 v6, 0, v6
	v_mul_f32_e32 v10, v2, v2
	v_max_f32_e32 v2, 0, v7
	v_mul_f32_e32 v7, v3, v3
	v_max_f32_e32 v3, 0, v8
	v_mul_f32_e32 v8, v4, v4
	v_max_f32_e32 v4, 0, v9
	v_mul_f32_e32 v2, v2, v2
	v_mul_f32_e32 v3, v3, v3
	v_mul_f32_e32 v4, v4, v4
	v_mul_f32_e32 v5, v5, v5
	s_mov_b64 s[12:13], -1
	s_andn2_b64 vcc, exec, s[40:41]
	v_mul_f32_e32 v6, v6, v6
	v_cvt_pk_bf16_f32 v2, v6, v2
	v_cvt_pk_bf16_f32 v3, v3, v4
	v_cvt_pk_bf16_f32 v4, v10, v7
	v_cvt_pk_bf16_f32 v5, v8, v5
	flat_store_dwordx4 v[18:19], v[2:5] offset:256 nt
	s_cbranch_vccnz .LBB0_553
	s_andn2_b64 vcc, exec, s[18:19]
	s_cbranch_vccnz .LBB0_552
	s_barrier
	s_branch .LBB0_552
